# grid barrier: first-arriving block of each XCD starts an asynchronous L2 write-back (leader's flush has less left), on top of v21
# baseline (speedup 1.0000x reference)
; __device__ __forceinline__ unsigned xb_ld(unsigned* p)              { return __hip_atomic_load(p, __ATOMIC_RELAXED, __HIP_MEMORY_SCOPE_AGENT); }
; __device__ __forceinline__ unsigned xb_add(unsigned* p, unsigned v) { return __hip_atomic_fetch_add(p, v, __ATOMIC_RELAXED, __HIP_MEMORY_SCOPE_AGENT); }
; #define XB_SPIN(cond, bar) do { unsigned _sp = 0; while (cond) { __builtin_amdgcn_s_sleep(1); \
;     if ((++_sp & 255u) == 0u) { if (xb_ld(&(bar)[XB_TMO])) break; if (_sp > XB_SPIN_CAP) { atomicAdd(&(bar)[XB_TMO], 1u); break; } } } } while (0)
; __device__ __forceinline__ void xcd_barrier(const XcdBarrier& b) {
;     ...
;         const unsigned old = xb_add(&bar[XB_XSUB(b.x)], 1u);
;         const unsigned gen = old / nloc;
;         if (old + 1u == (gen + 1u) * nloc) {
;             __builtin_amdgcn_fence(__ATOMIC_RELEASE, "agent");
;             asm volatile("s_waitcnt vmcnt(0)" ::: "memory");
;             const unsigned og = xb_add(&bar[XB_TOP], 1u);
;             const unsigned tg = og / nx;
;             if (og + 1u == (tg + 1u) * nx) xb_add(&bar[XB_TOPGEN], 1u);
;             else XB_SPIN(xb_ld(&bar[XB_TOPGEN]) == tg, bar);
;             __builtin_amdgcn_fence(__ATOMIC_ACQUIRE, "agent");
;             xb_add(&bar[XB_XGEN(b.x)], 1u);
;             asm volatile("s_waitcnt vmcnt(0)" ::: "memory");
;         } else {
;             XB_SPIN(xb_ld(&bar[XB_XGEN(b.x)]) == gen, bar);
;             __builtin_amdgcn_fence(__ATOMIC_ACQUIRE, "agent");
;             asm volatile("s_waitcnt vmcnt(0)" ::: "memory");
.LBB0_1088:
	s_or_b64 exec, exec, s[16:17]
	v_cvt_f32_u32_e32 v4, v2
	s_waitcnt vmcnt(0)
	v_readfirstlane_b32 s16, v3
	v_sub_u32_e32 v3, 0, v2
	v_rcp_iflag_f32_e32 v4, v4
	v_add_u32_e32 v5, s16, v1
	v_mul_f32_e32 v4, 0x4f7ffffe, v4
	v_cvt_u32_f32_e32 v4, v4
	v_mul_lo_u32 v1, v3, v4
	v_mul_hi_u32 v1, v4, v1
	v_add_u32_e32 v1, v4, v1
	v_mul_hi_u32 v1, v5, v1
	v_mul_lo_u32 v3, v1, v2
	v_sub_u32_e32 v3, v5, v3
	v_add_u32_e32 v4, 1, v1
	v_cmp_ge_u32_e32 vcc, v3, v2
	s_nop 1
	v_cndmask_b32_e32 v1, v1, v4, vcc
	v_sub_u32_e32 v4, v3, v2
	v_cndmask_b32_e32 v3, v3, v4, vcc
	v_add_u32_e32 v4, 1, v1
	v_cmp_ge_u32_e32 vcc, v3, v2
	v_add_u32_e32 v3, 1, v5
	s_nop 0
	v_cndmask_b32_e32 v1, v1, v4, vcc
	v_mul_lo_u32 v4, v2, v1
	v_add_u32_e32 v2, v4, v2
	v_cmp_ne_u32_e32 vcc, v3, v2
	s_and_saveexec_b64 s[16:17], vcc
	s_xor_b64 s[30:31], exec, s[16:17]
	s_cbranch_execz .LBB0_1102
	v_cmp_eq_u32_e32 vcc, v5, v4
	s_cbranch_vccz .Lmy_ewb
	buffer_wbl2 sc1
.Lmy_ewb:
	v_readlane_b32 s16, v254, 34
	v_readlane_b32 s17, v254, 35
	s_waitcnt lgkmcnt(0)
	s_nop 3
	global_load_dword v0, v177, s[16:17] sc1
	s_waitcnt vmcnt(0)
	v_cmp_eq_u32_e32 vcc, v0, v1
	s_and_saveexec_b64 s[34:35], vcc
	s_cbranch_execz .LBB0_1101
	s_mov_b32 s46, 1
	s_mov_b64 s[36:37], 0
	s_branch .LBB0_1092
